# QKV GEMM K-loop: the long load segments hand three of their six LDS-DMA pieces to the following MFMA block (issued between MFMAs), wait counts adjusted
# speedup vs baseline: 1.0022x; 1.0022x over previous
.LBB0_106:
	s_add_u32 s3, s4, 0xfffe0080
	s_addc_u32 s14, s5, -1
	s_cmp_eq_u32 s42, 4
	s_cselect_b32 s17, s7, s14
	s_cselect_b32 s16, s38, s3
	s_cselect_b32 s15, s9, s41
	s_cselect_b32 s14, s39, s40
	s_add_i32 s3, 0, 0x14000
	v_add_u32_e32 v92, s93, v182
	v_add_u32_e32 v124, s3, v182
	ds_read_b128 v[60:63], v92
	ds_read_b128 v[68:71], v92 offset:1024
	ds_read_b128 v[88:91], v92 offset:2048
	ds_read_b128 v[92:95], v92 offset:3072
	ds_read_b128 v[104:107], v124
	ds_read_b128 v[108:111], v124 offset:1024
	ds_read_b128 v[116:119], v124 offset:2048
	ds_read_b128 v[124:127], v124 offset:3072
	s_add_i32 m0, s23, 0xc000
	ds_read_b128 v[166:169], v183
	ds_read_b128 v[170:173], v183 offset:1024
	ds_read_b128 v[174:177], v183 offset:2048
	ds_read_b128 v[178:181], v183 offset:3072
	ds_read_b128 v[184:187], v183 offset:4096
	ds_read_b128 v[188:191], v183 offset:5120
	ds_read_b128 v[192:195], v183 offset:6144
	ds_read_b128 v[196:199], v183 offset:7168
	global_load_lds_dwordx4 v230, s[4:5]
	s_add_i32 m0, s23, 0xe000
	v_mov_b32_e32 v163, v231
	global_load_lds_dwordx4 v162, s[4:5]
	s_waitcnt vmcnt(8)
	s_waitcnt lgkmcnt(0)
	s_barrier
	s_setprio 1
	s_waitcnt lgkmcnt(0)
	v_mfma_i32_16x16x64_i8 v[156:159], v[60:63], v[166:169], v[156:159]
	v_mfma_i32_16x16x64_i8 v[152:155], v[88:91], v[166:169], v[152:155]
	v_mfma_i32_16x16x64_i8 v[140:143], v[60:63], v[174:177], v[140:143]
	v_mfma_i32_16x16x64_i8 v[136:139], v[88:91], v[174:177], v[136:139]
	v_mfma_i32_16x16x64_i8 v[120:123], v[60:63], v[184:187], v[120:123]
	v_mfma_i32_16x16x64_i8 v[112:115], v[88:91], v[184:187], v[112:115]
	v_mfma_i32_16x16x64_i8 v[84:87], v[60:63], v[192:195], v[84:87]
	v_mfma_i32_16x16x64_i8 v[80:83], v[88:91], v[192:195], v[80:83]
	v_mfma_i32_16x16x64_i8 v[156:159], v[68:71], v[170:173], v[156:159]
	v_mfma_i32_16x16x64_i8 v[152:155], v[92:95], v[170:173], v[152:155]
	v_mfma_i32_16x16x64_i8 v[140:143], v[68:71], v[178:181], v[140:143]
	v_mfma_i32_16x16x64_i8 v[136:139], v[92:95], v[178:181], v[136:139]
	v_mfma_i32_16x16x64_i8 v[120:123], v[68:71], v[188:191], v[120:123]
	v_mfma_i32_16x16x64_i8 v[112:115], v[92:95], v[188:191], v[112:115]
	v_mfma_i32_16x16x64_i8 v[84:87], v[68:71], v[196:199], v[84:87]
	v_mfma_i32_16x16x64_i8 v[80:83], v[92:95], v[196:199], v[80:83]
	s_setprio 0
	s_setprio 1
	v_mfma_i32_16x16x64_i8 v[148:151], v[104:107], v[166:169], v[148:151]
	v_mfma_i32_16x16x64_i8 v[144:147], v[116:119], v[166:169], v[144:147]
	v_mfma_i32_16x16x64_i8 v[132:135], v[104:107], v[174:177], v[132:135]
	v_mfma_i32_16x16x64_i8 v[128:131], v[116:119], v[174:177], v[128:131]
	v_mfma_i32_16x16x64_i8 v[100:103], v[104:107], v[184:187], v[100:103]
	v_mfma_i32_16x16x64_i8 v[96:99], v[116:119], v[184:187], v[96:99]
	v_mfma_i32_16x16x64_i8 v[76:79], v[104:107], v[192:195], v[76:79]
	v_mfma_i32_16x16x64_i8 v[72:75], v[116:119], v[192:195], v[72:75]
	v_mfma_i32_16x16x64_i8 v[148:151], v[108:111], v[170:173], v[148:151]
	v_mfma_i32_16x16x64_i8 v[144:147], v[124:127], v[170:173], v[144:147]
	v_mfma_i32_16x16x64_i8 v[132:135], v[108:111], v[178:181], v[132:135]
	v_mfma_i32_16x16x64_i8 v[128:131], v[124:127], v[178:181], v[128:131]
	v_mfma_i32_16x16x64_i8 v[100:103], v[108:111], v[188:191], v[100:103]
	v_mfma_i32_16x16x64_i8 v[96:99], v[124:127], v[188:191], v[96:99]
	v_mfma_i32_16x16x64_i8 v[76:79], v[108:111], v[196:199], v[76:79]
	v_mfma_i32_16x16x64_i8 v[72:75], v[124:127], v[196:199], v[72:75]
	s_setprio 0
	s_barrier
	s_add_i32 s43, s93, s22
	s_mov_b32 m0, s43
	ds_read_b128 v[166:169], v183 offset:16384
	ds_read_b128 v[170:173], v183 offset:17408
	ds_read_b128 v[174:177], v183 offset:18432
	ds_read_b128 v[178:181], v183 offset:19456
	ds_read_b128 v[184:187], v183 offset:20480
	ds_read_b128 v[188:191], v183 offset:21504
	ds_read_b128 v[192:195], v183 offset:22528
	ds_read_b128 v[196:199], v183 offset:23552
	global_load_lds_dwordx4 v160, s[14:15]
	s_add_i32 m0, s43, 0x2000
	s_add_u32 s44, s14, 0x20000
	s_addc_u32 s45, s15, 0
	s_add_i32 s3, s3, s22
	global_load_lds_dwordx4 v164, s[14:15]
	s_mov_b32 m0, s3
	v_mov_b32_e32 v161, v231
	global_load_lds_dwordx4 v160, s[44:45]
	v_mov_b32_e32 v165, v231
	v_lshl_add_u64 v[200:201], s[14:15], 0, v[160:161]
	v_lshl_add_u64 v[202:203], s[14:15], 0, v[164:165]
	s_waitcnt vmcnt(5)
	s_waitcnt lgkmcnt(0)
	v_lshl_add_u64 v[204:205], s[16:17], 0, v[230:231]
	v_lshl_add_u64 v[206:207], s[16:17], 0, v[162:163]
	s_barrier
	s_setprio 1
	s_waitcnt lgkmcnt(0)
	v_mfma_i32_16x16x64_i8 v[64:67], v[60:63], v[166:169], v[64:67]
	v_mfma_i32_16x16x64_i8 v[56:59], v[88:91], v[166:169], v[56:59]
	v_mfma_i32_16x16x64_i8 v[44:47], v[60:63], v[174:177], v[44:47]
	v_mfma_i32_16x16x64_i8 v[40:43], v[88:91], v[174:177], v[40:43]
	s_add_i32 m0, s3, 0x2000
	s_nop 0
	global_load_lds_dwordx4 v164, s[44:45]
	v_mfma_i32_16x16x64_i8 v[28:31], v[60:63], v[184:187], v[28:31]
	v_mfma_i32_16x16x64_i8 v[24:27], v[88:91], v[184:187], v[24:27]
	v_mfma_i32_16x16x64_i8 v[12:15], v[60:63], v[192:195], v[12:15]
	v_mfma_i32_16x16x64_i8 v[8:11], v[88:91], v[192:195], v[8:11]
	v_mfma_i32_16x16x64_i8 v[64:67], v[68:71], v[170:173], v[64:67]
	v_mfma_i32_16x16x64_i8 v[56:59], v[92:95], v[170:173], v[56:59]
	v_mfma_i32_16x16x64_i8 v[44:47], v[68:71], v[178:181], v[44:47]
	v_mfma_i32_16x16x64_i8 v[40:43], v[92:95], v[178:181], v[40:43]
	s_mov_b32 m0, s23
	s_nop 0
	global_load_lds_dwordx4 v230, s[16:17]
	v_mfma_i32_16x16x64_i8 v[28:31], v[68:71], v[188:191], v[28:31]
	v_mfma_i32_16x16x64_i8 v[24:27], v[92:95], v[188:191], v[24:27]
	v_mfma_i32_16x16x64_i8 v[12:15], v[68:71], v[196:199], v[12:15]
	v_mfma_i32_16x16x64_i8 v[8:11], v[92:95], v[196:199], v[8:11]
	s_setprio 0
	s_setprio 1
	v_mfma_i32_16x16x64_i8 v[52:55], v[104:107], v[166:169], v[52:55]
	v_mfma_i32_16x16x64_i8 v[48:51], v[116:119], v[166:169], v[48:51]
	v_mfma_i32_16x16x64_i8 v[36:39], v[104:107], v[174:177], v[36:39]
	v_mfma_i32_16x16x64_i8 v[32:35], v[116:119], v[174:177], v[32:35]
	s_mov_b32 m0, s24
	s_nop 0
	global_load_lds_dwordx4 v162, s[16:17]
	v_mfma_i32_16x16x64_i8 v[20:23], v[104:107], v[184:187], v[20:23]
	v_mfma_i32_16x16x64_i8 v[16:19], v[116:119], v[184:187], v[16:19]
	v_mfma_i32_16x16x64_i8 v[4:7], v[104:107], v[192:195], v[4:7]
	v_mfma_i32_16x16x64_i8 v[0:3], v[116:119], v[192:195], v[0:3]
	v_mfma_i32_16x16x64_i8 v[52:55], v[108:111], v[170:173], v[52:55]
	v_mfma_i32_16x16x64_i8 v[48:51], v[124:127], v[170:173], v[48:51]
	v_mfma_i32_16x16x64_i8 v[36:39], v[108:111], v[178:181], v[36:39]
	v_mfma_i32_16x16x64_i8 v[32:35], v[124:127], v[178:181], v[32:35]
	v_mfma_i32_16x16x64_i8 v[20:23], v[108:111], v[188:191], v[20:23]
	v_mfma_i32_16x16x64_i8 v[16:19], v[124:127], v[188:191], v[16:19]
	v_mfma_i32_16x16x64_i8 v[4:7], v[108:111], v[196:199], v[4:7]
	v_mfma_i32_16x16x64_i8 v[0:3], v[124:127], v[196:199], v[0:3]
	s_setprio 0
	s_barrier
	s_add_i32 s3, 0, 0x1c000
	v_add_u32_e32 v92, s2, v182
	v_add_u32_e32 v124, s3, v182
	ds_read_b128 v[60:63], v92
	ds_read_b128 v[68:71], v92 offset:1024
	ds_read_b128 v[88:91], v92 offset:2048
	ds_read_b128 v[92:95], v92 offset:3072
	ds_read_b128 v[104:107], v124
	ds_read_b128 v[108:111], v124 offset:1024
	ds_read_b128 v[116:119], v124 offset:2048
	ds_read_b128 v[124:127], v124 offset:3072
	s_add_u32 s16, s16, 0x20000
	s_addc_u32 s17, s17, 0
	s_mov_b32 m0, s25
	ds_read_b128 v[166:169], v183 offset:32768
	ds_read_b128 v[170:173], v183 offset:33792
	ds_read_b128 v[174:177], v183 offset:34816
	ds_read_b128 v[178:181], v183 offset:35840
	ds_read_b128 v[184:187], v183 offset:36864
	ds_read_b128 v[188:191], v183 offset:37888
	ds_read_b128 v[192:195], v183 offset:38912
	ds_read_b128 v[196:199], v183 offset:39936
	global_load_lds_dwordx4 v230, s[16:17]
	s_mov_b32 m0, s26
	s_nop 0
	global_load_lds_dwordx4 v162, s[16:17]
	s_waitcnt vmcnt(8)
	s_waitcnt lgkmcnt(0)
	s_barrier
	s_setprio 1
	s_waitcnt lgkmcnt(0)
	v_mfma_i32_16x16x64_i8 v[156:159], v[60:63], v[166:169], v[156:159]
	v_mfma_i32_16x16x64_i8 v[152:155], v[88:91], v[166:169], v[152:155]
	v_mfma_i32_16x16x64_i8 v[140:143], v[60:63], v[174:177], v[140:143]
	v_mfma_i32_16x16x64_i8 v[136:139], v[88:91], v[174:177], v[136:139]
	v_mfma_i32_16x16x64_i8 v[120:123], v[60:63], v[184:187], v[120:123]
	v_mfma_i32_16x16x64_i8 v[112:115], v[88:91], v[184:187], v[112:115]
	v_mfma_i32_16x16x64_i8 v[84:87], v[60:63], v[192:195], v[84:87]
	v_mfma_i32_16x16x64_i8 v[80:83], v[88:91], v[192:195], v[80:83]
	v_mfma_i32_16x16x64_i8 v[156:159], v[68:71], v[170:173], v[156:159]
	v_mfma_i32_16x16x64_i8 v[152:155], v[92:95], v[170:173], v[152:155]
	v_mfma_i32_16x16x64_i8 v[140:143], v[68:71], v[178:181], v[140:143]
	v_mfma_i32_16x16x64_i8 v[136:139], v[92:95], v[178:181], v[136:139]
	v_mfma_i32_16x16x64_i8 v[120:123], v[68:71], v[188:191], v[120:123]
	v_mfma_i32_16x16x64_i8 v[112:115], v[92:95], v[188:191], v[112:115]
	v_mfma_i32_16x16x64_i8 v[84:87], v[68:71], v[196:199], v[84:87]
	v_mfma_i32_16x16x64_i8 v[80:83], v[92:95], v[196:199], v[80:83]
	s_setprio 0
	s_setprio 1
	v_mfma_i32_16x16x64_i8 v[148:151], v[104:107], v[166:169], v[148:151]
	v_mfma_i32_16x16x64_i8 v[144:147], v[116:119], v[166:169], v[144:147]
	v_mfma_i32_16x16x64_i8 v[132:135], v[104:107], v[174:177], v[132:135]
	v_mfma_i32_16x16x64_i8 v[128:131], v[116:119], v[174:177], v[128:131]
	v_mfma_i32_16x16x64_i8 v[100:103], v[104:107], v[184:187], v[100:103]
	v_mfma_i32_16x16x64_i8 v[96:99], v[116:119], v[184:187], v[96:99]
	v_mfma_i32_16x16x64_i8 v[76:79], v[104:107], v[192:195], v[76:79]
	v_mfma_i32_16x16x64_i8 v[72:75], v[116:119], v[192:195], v[72:75]
	v_mfma_i32_16x16x64_i8 v[148:151], v[108:111], v[170:173], v[148:151]
	v_mfma_i32_16x16x64_i8 v[144:147], v[124:127], v[170:173], v[144:147]
	v_mfma_i32_16x16x64_i8 v[132:135], v[108:111], v[178:181], v[132:135]
	v_mfma_i32_16x16x64_i8 v[128:131], v[124:127], v[178:181], v[128:131]
	v_mfma_i32_16x16x64_i8 v[100:103], v[108:111], v[188:191], v[100:103]
	v_mfma_i32_16x16x64_i8 v[96:99], v[124:127], v[188:191], v[96:99]
	v_mfma_i32_16x16x64_i8 v[76:79], v[108:111], v[196:199], v[76:79]
	v_mfma_i32_16x16x64_i8 v[72:75], v[124:127], v[196:199], v[72:75]
	s_setprio 0
	s_barrier
	s_add_i32 s16, s2, s22
	v_lshl_add_u64 v[200:201], v[200:201], 0, s[96:97]
	s_mov_b32 m0, s16
	ds_read_b128 v[166:169], v183 offset:49152
	ds_read_b128 v[170:173], v183 offset:50176
	ds_read_b128 v[174:177], v183 offset:51200
	ds_read_b128 v[178:181], v183 offset:52224
	ds_read_b128 v[184:187], v183 offset:53248
	ds_read_b128 v[188:191], v183 offset:54272
	ds_read_b128 v[192:195], v183 offset:55296
	ds_read_b128 v[196:199], v183 offset:56320
	global_load_lds_dwordx4 v[200:201], off
	s_add_i32 m0, s16, 0x2000
	s_add_u32 s14, s14, 0x20080
	v_lshl_add_u64 v[200:201], v[202:203], 0, s[96:97]
	s_addc_u32 s15, s15, 0
	s_add_i32 s3, s3, s22
	global_load_lds_dwordx4 v[200:201], off
	s_mov_b32 m0, s3
	v_lshl_add_u64 v[200:201], v[204:205], 0, s[96:97]
	global_load_lds_dwordx4 v160, s[14:15]
	s_waitcnt vmcnt(5)
	s_waitcnt lgkmcnt(0)
	s_barrier
	s_setprio 1
	s_waitcnt lgkmcnt(0)
	v_mfma_i32_16x16x64_i8 v[64:67], v[60:63], v[166:169], v[64:67]
	v_mfma_i32_16x16x64_i8 v[56:59], v[88:91], v[166:169], v[56:59]
	v_mfma_i32_16x16x64_i8 v[44:47], v[60:63], v[174:177], v[44:47]
	v_mfma_i32_16x16x64_i8 v[40:43], v[88:91], v[174:177], v[40:43]
	s_add_i32 m0, s3, 0x2000
	s_nop 0
	global_load_lds_dwordx4 v164, s[14:15]
	v_mfma_i32_16x16x64_i8 v[28:31], v[60:63], v[184:187], v[28:31]
	v_mfma_i32_16x16x64_i8 v[24:27], v[88:91], v[184:187], v[24:27]
	v_mfma_i32_16x16x64_i8 v[12:15], v[60:63], v[192:195], v[12:15]
	v_mfma_i32_16x16x64_i8 v[8:11], v[88:91], v[192:195], v[8:11]
	v_mfma_i32_16x16x64_i8 v[64:67], v[68:71], v[170:173], v[64:67]
	v_mfma_i32_16x16x64_i8 v[56:59], v[92:95], v[170:173], v[56:59]
	v_mfma_i32_16x16x64_i8 v[44:47], v[68:71], v[178:181], v[44:47]
	v_mfma_i32_16x16x64_i8 v[40:43], v[92:95], v[178:181], v[40:43]
	s_mov_b32 m0, s31
	s_nop 0
	global_load_lds_dwordx4 v[200:201], off
	v_mfma_i32_16x16x64_i8 v[28:31], v[68:71], v[188:191], v[28:31]
	v_mfma_i32_16x16x64_i8 v[24:27], v[92:95], v[188:191], v[24:27]
	v_mfma_i32_16x16x64_i8 v[12:15], v[68:71], v[196:199], v[12:15]
	v_mfma_i32_16x16x64_i8 v[8:11], v[92:95], v[196:199], v[8:11]
	s_setprio 0
	s_setprio 1
	v_mfma_i32_16x16x64_i8 v[52:55], v[104:107], v[166:169], v[52:55]
	v_mfma_i32_16x16x64_i8 v[48:51], v[116:119], v[166:169], v[48:51]
	v_mfma_i32_16x16x64_i8 v[36:39], v[104:107], v[174:177], v[36:39]
	v_mfma_i32_16x16x64_i8 v[32:35], v[116:119], v[174:177], v[32:35]
	v_lshl_add_u64 v[200:201], v[206:207], 0, s[96:97]
	s_mov_b32 m0, s33
	s_nop 0
	global_load_lds_dwordx4 v[200:201], off
	v_mfma_i32_16x16x64_i8 v[20:23], v[104:107], v[184:187], v[20:23]
	v_mfma_i32_16x16x64_i8 v[16:19], v[116:119], v[184:187], v[16:19]
	v_mfma_i32_16x16x64_i8 v[4:7], v[104:107], v[192:195], v[4:7]
	v_mfma_i32_16x16x64_i8 v[0:3], v[116:119], v[192:195], v[0:3]
	v_mfma_i32_16x16x64_i8 v[52:55], v[108:111], v[170:173], v[52:55]
	v_mfma_i32_16x16x64_i8 v[48:51], v[124:127], v[170:173], v[48:51]
	v_mfma_i32_16x16x64_i8 v[36:39], v[108:111], v[178:181], v[36:39]
	v_mfma_i32_16x16x64_i8 v[32:35], v[124:127], v[178:181], v[32:35]
	v_mfma_i32_16x16x64_i8 v[20:23], v[108:111], v[188:191], v[20:23]
	v_mfma_i32_16x16x64_i8 v[16:19], v[124:127], v[188:191], v[16:19]
	v_mfma_i32_16x16x64_i8 v[4:7], v[108:111], v[196:199], v[4:7]
	v_mfma_i32_16x16x64_i8 v[0:3], v[124:127], v[196:199], v[0:3]
	s_setprio 0
	s_barrier
	s_add_i32 s42, s42, 2
	s_add_u32 s4, s4, 0x100
	s_addc_u32 s5, s5, 0
	s_add_u32 s40, s40, 0x100
	s_addc_u32 s41, s41, 0
	s_cmp_gt_u32 s42, 5
	s_cbranch_scc0 .LBB0_106
	s_ashr_i32 s4, s36, 31
	s_lshr_b32 s4, s4, 30
	s_add_i32 s4, s36, s4
	s_mul_i32 s3, s37, 0xc00
	s_ashr_i32 s4, s4, 2
	s_add_i32 s3, s3, 0
	s_ashr_i32 s5, s4, 31
	s_add_i32 s3, s3, 0x20340
	s_lshl_b32 s7, s36, 8
	s_lshl_b32 s9, s4, 10
	s_lshl_b64 s[4:5], s[4:5], 25
	v_mbcnt_lo_u32_b32 v60, -1, 0
	v_mbcnt_hi_u32_b32 v60, -1, v60
	s_add_u32 s4, s64, s4
	v_and_b32_e32 v161, 15, v60
	v_ashrrev_i32_e32 v163, 4, v60
	s_addc_u32 s5, s65, s5
	v_lshl_add_u32 v124, v163, 3, s28
	s_sub_i32 s7, s7, s9
	v_lshl_add_u32 v126, v124, 2, s3
	v_add_u32_e32 v124, s7, v124
	v_add_u32_e32 v168, s27, v161
	v_ashrrev_i32_e32 v125, 31, v124
	ds_read_b128 v[104:107], v126 offset:16
	ds_read_b128 v[88:91], v126 offset:512
	ds_read_b128 v[108:111], v126 offset:1040
	ds_read_b128 v[68:71], v126 offset:1536
	ds_read_b128 v[116:119], v126 offset:1024
	ds_read_b128 v[92:95], v126 offset:528
	ds_read_b128 v[60:63], v126 offset:1552
	v_lshl_add_u64 v[166:167], v[124:125], 1, s[4:5]
	v_lshl_add_u32 v165, v168, 2, s3
	ds_read_b128 v[124:127], v126
	ds_read_b32 v174, v165 offset:2048
	v_cvt_f32_i32_e32 v171, v158
	v_cvt_f32_i32_e32 v170, v156
	v_cvt_f32_i32_e32 v179, v159
	v_cvt_f32_i32_e32 v178, v157
	s_waitcnt lgkmcnt(0)
	v_mov_b32_e32 v156, v116
	v_pk_mul_f32 v[176:177], v[174:175], v[170:171] op_sel_hi:[0,1]
	v_mov_b32_e32 v170, v124
	v_mov_b32_e32 v171, v126
	v_mov_b32_e32 v157, v118
	v_pk_fma_f32 v[158:159], v[176:177], v[170:171], v[156:157]
	v_pk_mul_f32 v[176:177], v[174:175], v[178:179] op_sel_hi:[0,1]
	v_cvt_f32_i32_e32 v179, v152
	v_cvt_f32_i32_e32 v178, v154
	v_cvt_f32_i32_e32 v181, v153
	v_cvt_f32_i32_e32 v180, v155
	v_lshl_add_u32 v168, s35, 8, v168
	s_and_b32 s4, s36, -4
	v_ashrrev_i32_e32 v169, 31, v168
	s_cmp_eq_u32 s4, 4
	v_lshlrev_b64 v[172:173], 11, v[168:169]
	v_mov_b32_e32 v126, v125
	v_mov_b32_e32 v118, v117
	v_pk_mul_f32 v[178:179], v[174:175], v[178:179] op_sel_hi:[0,1]
	v_mov_b32_e32 v116, v106
	v_mov_b32_e32 v117, v104
	v_mov_b32_e32 v124, v110
	v_mov_b32_e32 v125, v108
	v_pk_mul_f32 v[154:155], v[174:175], v[180:181] op_sel_hi:[0,1]
	v_mov_b32_e32 v104, v107
	v_mov_b32_e32 v108, v111
	s_cselect_b64 s[14:15], -1, 0
	s_cmp_lg_u32 s4, 4
	v_lshl_add_u64 v[172:173], v[166:167], 0, v[172:173]
	v_pk_fma_f32 v[176:177], v[176:177], v[126:127], v[118:119]
	v_pk_fma_f32 v[152:153], v[178:179], v[116:117], v[124:125]
	v_pk_fma_f32 v[106:107], v[154:155], v[104:105], v[108:109]
	v_cvt_pk_bf16_f32 v178, v158, v176
	v_cvt_pk_bf16_f32 v179, v159, v177
	s_nop 0
	v_cvt_pk_bf16_f32 v180, v153, v107
	v_cvt_pk_bf16_f32 v181, v152, v106
	global_store_dwordx4 v[172:173], v[178:181], off sc1
	s_cbranch_scc1 .LBB0_109
	v_pk_mul_f32 v[110:111], v[176:177], v[176:177]
	v_pk_mul_f32 v[106:107], v[106:107], v[106:107]
	v_pk_fma_f32 v[110:111], v[158:159], v[158:159], v[110:111]
	v_pk_fma_f32 v[106:107], v[152:153], v[152:153], v[106:107]
	v_add_f32_e32 v110, v110, v111
	v_add_f32_e32 v107, v107, v110
	v_add_f32_e32 v106, v106, v107
	v_max_f32_e32 v106, 0, v106
	s_branch .LBB0_110
